# attention unit prologue: the four Q-stash loads issued together (were four serialized load-wait-ds_write round trips) and drained after the first K/V tile loads are in flight
# baseline (speedup 1.0000x reference)
; __device__ __forceinline__ void attn_unit(LAS unsigned char* lds, const bf16* Qh, const bf16* Kh, const bf16* VTh, const float* nrm, bf16* Y, const float* subln, float lam, int b, int h, int qb) {
;     ...
;     const int tid = tid_, lane = tid & 63, r32 = lane & 31, hi = lane >> 5, wid = __builtin_amdgcn_readfirstlane(tid >> 6);
;     const int wq = wid & 3, comp = wid >> 2;
;     const size_t tokb = (size_t)b * SEQ; const int q0 = qb * 128, qw0 = q0 + wq * 32;
;     const int bh = b * 16 + h;
;     const int qso = OFF_Q + wid * 4096 + lane * 16;
;     { const bf16* qp = Qh + ((size_t)bh * 4096 + qw0 + r32) * 128 + comp * 64 + hi * 8;
; #pragma unroll
;       for (int d0 = 0; d0 < 4; ++d0) *(LAS bf16x8*)(lds + qso + d0 * 1024) = *(const bf16x8*)(qp + d0 * 16); }
;     const char* kgb = (const char*)(Kh + (size_t)bh * 4096 * 128);
;     const char* vgb = (const char*)(VTh + (size_t)bh * 4096 * 128);
;     const unsigned goff = (unsigned)tid * 16u;
;     const int kl0 = OFF_K + (tid >> 4) * KROW + (tid & 15) * 16, vl0 = OFF_V + (tid >> 3) * VROW + (tid & 7) * 16;
;     const int sig = (r32 & ~12) | ((r32 & 4) << 1) | ((r32 & 8) >> 1);
;     const int kfo = OFF_K + sig * KROW + comp * 128 + hi * 16;
;     const int vfo = OFF_V + r32 * VROW + hi * 16;
;     LAS float* wsf = (LAS float*)(lds + OFF_WS) + wid * 64;
;     LAS float* tminb = (LAS float*)(lds + OFF_TMIN);
;     const float slope2 = exp2f(-0.5f * (float)(h + 1)) * LOG2E;
;     const int qpos = qw0 + r32;
;     const int u0 = 2 * qb, u1 = 2 * qb + 1, u2 = (qb == 0) ? 2 : (qb == 31 ? 61 : 2 * qb - 1), u3 = (qb == 0) ? 3 : (qb == 31 ? 60 : 2 * qb + 2);
;     int ktv = (lane == 0) ? u0 : (lane == 1) ? u1 : (lane == 2) ? u2 : u3;
;     const float* nb = nrm + (size_t)b * 64 * 64;
;     const float k2a = nb[lane * 64 + 32 + 2 * h], k2b = nb[lane * 64 + 32 + 2 * h + 1];
;     const float q2a = fmaxf(nb[u0 * 64 + 2 * h], nb[u1 * 64 + 2 * h]), q2b = fmaxf(nb[u0 * 64 + 2 * h + 1], nb[u1 * 64 + 2 * h + 1]);
;     f32x16 o[4];
; #pragma unroll
;     for (int i = 0; i < 4; ++i) o[i] = f32x16{};
;     float mhat = 0.f, lsum = 0.f, tmax = -INFINITY; bool resc = false;
;     v4u pw[4] = {};
;     v4u kreg[2], vreg[2];
;     ...
;     ATT_LOAD(u0); ATT_STORE(0); ATT_LOAD(u1);
; __global__ void __launch_bounds__(NWAVES * 64, 2) mega_fwd(Args args) {
;     ...
;             __syncthreads();
;             const int unit = *uq;
.LBB0_911:
	s_or_b64 exec, exec, s[10:11]
	v_mov_b32_e32 v0, s94
	s_waitcnt lgkmcnt(0)
	s_barrier
	ds_read_b32 v0, v0
	s_waitcnt lgkmcnt(0)
	v_cmp_gt_i32_e32 vcc, 0, v0
	v_readfirstlane_b32 s0, v0
	s_cbranch_vccnz .LBB0_921
	s_lshr_b32 s1, s0, 8
	s_and_b32 s3, s0, 0x80
	s_sub_i32 s5, 15, s1
	v_mov_b32_e32 v6, v248
	s_cmp_eq_u32 s3, 0
	s_cselect_b32 s5, s5, s1
	v_readfirstlane_b32 s81, v6
	s_ashr_i32 s1, s81, 6
	s_and_b32 s3, s0, 31
	s_and_b32 s14, s1, 3
	s_bfe_u32 s80, s0, 0x20005
	s_lshl_b32 s0, s3, 7
	s_lshl_b32 s6, s14, 5
	s_or_b32 s18, s6, s0
	s_lshl_b32 s6, s80, 4
	s_add_i32 s6, s6, s5
	s_ashr_i32 s7, s6, 31
	s_lshl_b64 s[10:11], s[6:7], 12
	v_and_b32_e32 v202, 31, v6
	s_or_b32 s10, s10, s18
	s_ashr_i32 s15, s81, 8
	v_or_b32_e32 v0, s10, v202
	v_mov_b32_e32 v1, s11
	v_lshlrev_b64 v[0:1], 8, v[0:1]
	s_lshl_b32 s10, s15, 6
	v_bfe_u32 v201, v6, 5, 1
	v_lshl_add_u64 v[0:1], s[26:27], 0, v[0:1]
	s_ashr_i32 s11, s10, 31
	v_and_b32_e32 v203, 63, v6
	v_lshl_add_u64 v[0:1], s[10:11], 1, v[0:1]
	v_lshlrev_b32_e32 v180, 4, v201
	v_mov_b32_e32 v181, v177
	v_lshl_add_u64 v[4:5], v[0:1], 0, v[180:181]
	v_lshl_add_u32 v0, v203, 4, 0
	s_lshl_b32 s12, s1, 12
	v_add_u32_e32 v0, 0x1ac80, v0
	v_add_u32_e32 v210, s12, v0
	global_load_dwordx4 v[128:131], v[4:5], off
	global_load_dwordx4 v[132:135], v[4:5], off offset:32
	global_load_dwordx4 v[136:139], v[4:5], off offset:64
	global_load_dwordx4 v[140:143], v[4:5], off offset:96
	s_lshl_b64 s[12:13], s[6:7], 20
	s_movk_i32 s6, 0x110
	s_add_u32 s68, s38, s12
	s_addc_u32 s69, s39, s13
	s_lshl_b32 s64, s15, 7
	v_lshlrev_b32_e32 v176, 6, v203
	v_lshlrev_b32_e32 v216, 4, v6
	v_lshl_add_u32 v8, s3, 15, v216
	v_add_u32_e32 v12, 0x2000, v8
	v_and_b32_e32 v32, 0xf0, v216
	v_and_b32_e32 v34, 0x70, v216
	v_lshlrev_b32_e32 v209, 3, v201
	v_or_b32_e32 v212, s18, v202
	v_lshrrev_b32_e32 v0, 4, v6
	v_mul_lo_u32 v30, v0, s6
	v_lshrrev_b32_e32 v0, 3, v6
	v_lshlrev_b32_e32 v1, 1, v6
	v_lshrrev_b32_e32 v2, 1, v6
	v_mul_lo_u32 v31, v0, s83
	v_and_b32_e32 v0, 19, v6
	v_and_b32_e32 v1, 8, v1
	v_and_b32_e32 v2, 4, v2
	s_add_i32 s6, s5, 1
	v_or3_b32 v2, v0, v1, v2
	v_cvt_f32_i32_e32 v0, s6
	s_mov_b32 s6, 0xc2fc0000
	v_mul_u32_u24_e32 v33, 0x110, v2
	v_add3_u32 v16, 0, v30, v32
	v_mul_f32_e32 v1, -0.5, v0
	v_cmp_gt_f32_e32 vcc, s6, v1
	s_and_b64 s[6:7], vcc, exec
	s_cselect_b32 s6, 0xffffffc0, 0
	v_cndmask_b32_e32 v1, 0, v249, vcc
	v_fmac_f32_e32 v1, -0.5, v0
	v_exp_f32_e32 v0, v1
	v_cmp_eq_u32_e32 vcc, 1, v203
	v_ldexp_f32 v0, v0, s6
	s_lshl_b32 s6, s3, 1
	s_or_b32 s24, s6, 1
	s_add_i32 s7, s6, -1
	s_add_i32 s10, s6, 2
	s_cmp_lg_u32 s3, 31
	s_cselect_b32 s10, s10, 60
	s_cmp_eq_u32 s3, 0
	s_cselect_b32 s33, 2, s7
	s_cselect_b32 s25, 3, s10
	v_mul_f32_e32 v208, 0x3fb8aa3b, v0
	v_cmp_eq_u32_e64 s[10:11], 2, v203
	v_mov_b32_e32 v0, s25
	v_mov_b32_e32 v1, s33
	s_lshl_b32 s7, s80, 14
	v_cndmask_b32_e64 v0, v0, v1, s[10:11]
	s_add_u32 s10, s35, s7
	s_addc_u32 s11, s92, 0
	s_lshl_b32 s16, s5, 1
	s_add_i32 s66, s16, s0
	s_ashr_i32 s67, s66, 31
	s_ashr_i32 s17, s16, 31
	s_lshl_b64 s[66:67], s[66:67], 2
	s_add_u32 s66, s10, s66
	v_mov_b32_e32 v1, s24
	s_addc_u32 s67, s11, s67
	s_lshl_b32 s7, s24, 6
	v_cndmask_b32_e32 v3, v0, v1, vcc
	v_lshl_add_u64 v[0:1], s[16:17], 0, v[176:177]
	s_add_i32 s16, s7, s16
	s_ashr_i32 s17, s16, 31
	s_lshl_b64 s[16:17], s[16:17], 2
	v_lshl_add_u64 v[0:1], v[0:1], 2, s[10:11]
	s_add_u32 s10, s10, s16
	s_addc_u32 s11, s11, s17
	s_add_u32 s70, s42, s12
	global_load_dwordx2 v[24:25], v[0:1], off offset:128
	global_load_dwordx2 v[26:27], v177, s[66:67]
	s_addc_u32 s71, s43, s13
	v_cmp_eq_u32_e64 s[12:13], 0, v203
	v_mov_b32_e32 v0, s6
	global_load_dwordx2 v[28:29], v177, s[10:11]
	v_cndmask_b32_e64 v213, v3, v0, s[12:13]
	global_load_dwordx4 v[0:3], v8, s[70:71]
	global_load_dwordx4 v[4:7], v12, s[70:71]
	s_nop 0
	global_load_dwordx4 v[8:11], v8, s[68:69]
	s_nop 0
	global_load_dwordx4 v[12:15], v12, s[68:69]
	v_readlane_b32 s3, v213, 2
	s_add_i32 s7, s64, 0
	v_add3_u32 v217, s7, v33, v180
	s_waitcnt vmcnt(7)
	ds_write_b128 v210, v[128:131]
	ds_write_b128 v210, v[132:135] offset:1024
	ds_write_b128 v210, v[136:139] offset:2048
	ds_write_b128 v210, v[140:143] offset:3072
	s_waitcnt vmcnt(3)
	ds_write_b128 v16, v[0:3]
	s_waitcnt vmcnt(2)
	ds_write_b128 v16, v[4:7] offset:8704
	v_add3_u32 v0, 0, v31, v34
	s_waitcnt vmcnt(1)
	ds_write_b128 v0, v[8:11] offset:52224
	s_waitcnt vmcnt(0)
	ds_write_b128 v0, v[12:15] offset:61440
	v_lshl_add_u32 v8, s24, 14, v216
	v_add_u32_e32 v12, 0x2000, v8
	v_add_u32_e32 v17, 0xcc00, v0
	global_load_dwordx4 v[0:3], v8, s[70:71]
	global_load_dwordx4 v[4:7], v12, s[70:71]
	s_nop 0
	global_load_dwordx4 v[8:11], v8, s[68:69]
	s_nop 0
	global_load_dwordx4 v[12:15], v12, s[68:69]
	s_waitcnt lgkmcnt(0)
	s_barrier
	s_waitcnt vmcnt(3)
	ds_write_b128 v16, v[0:3] offset:17408
	s_waitcnt vmcnt(2)
	ds_write_b128 v16, v[4:7] offset:26112
	s_waitcnt vmcnt(1)
	ds_write_b128 v17, v[8:11] offset:18432
	s_waitcnt vmcnt(0)
	ds_write_b128 v17, v[12:15] offset:27648
	v_lshl_add_u32 v0, s3, 14, v216
	v_add_u32_e32 v1, 0x2000, v0
	global_load_dwordx4 v[128:131], v0, s[70:71]
	global_load_dwordx4 v[132:135], v1, s[70:71]
	global_load_dwordx4 v[136:139], v0, s[68:69]
	global_load_dwordx4 v[140:143], v1, s[68:69]
	v_readlane_b32 s3, v213, 0
	s_lshl_b32 s3, s3, 6
	s_or_b32 s7, s3, 63
	v_or_b32_e32 v0, s3, v209
	v_sub_u32_e32 v16, v212, v0
	ds_read_b128 v[12:15], v210
	ds_read_b128 v[8:11], v210 offset:1024
	ds_read_b128 v[4:7], v210 offset:2048
	ds_read_b128 v[0:3], v210 offset:3072
	s_cmp_lt_i32 s7, s18
	v_cvt_f32_i32_e32 v35, v16
	ds_read_b128 v[20:23], v217
	ds_read_b128 v[16:19], v217 offset:8704
	s_cselect_b64 s[10:11], -1, 0
	s_or_b32 s7, s18, 31
	s_cmp_gt_i32 s3, s7
	s_cselect_b64 s[16:17], -1, 0
	s_or_b64 s[66:67], s[10:11], s[16:17]
	s_mov_b64 s[16:17], -1
	s_andn2_b64 vcc, exec, s[66:67]
	s_cbranch_vccz .LBB0_914
	v_add_f32_e32 v36, v35, v179
	v_xor_b32_e32 v39, 0x80000000, v208
	v_add_f32_e32 v37, v36, v179
	v_fma_f32 v72, |v36|, v39, v184
	v_add_f32_e32 v40, v35, v185
	v_add_f32_e32 v36, v36, v185
	v_fma_f32 v64, |v35|, v39, v184
	s_mov_b64 s[16:17], 0
	v_add_f32_e32 v38, v37, v179
	v_fma_f32 v80, |v37|, v39, v184
	v_add_f32_e32 v37, v37, v185
	v_fma_f32 v65, |v40|, v39, v184
	v_fma_f32 v73, |v36|, v39, v184
	v_add_f32_e32 v40, v40, v185
	v_fma_f32 v88, |v38|, v39, v184
	v_add_f32_e32 v38, v38, v185
	v_fma_f32 v81, |v37|, v39, v184
	v_add_f32_e32 v36, v36, v185
	v_add_f32_e32 v37, v37, v185
	v_fma_f32 v66, |v40|, v39, v184
	v_add_f32_e32 v40, v40, v185
	v_fma_f32 v89, |v38|, v39, v184
	v_add_f32_e32 v38, v38, v185
	v_fma_f32 v74, |v36|, v39, v184
	v_fma_f32 v82, |v37|, v39, v184
	v_add_f32_e32 v36, v36, v185
	v_add_f32_e32 v37, v37, v185
	v_fma_f32 v67, |v40|, v39, v184
	v_fma_f32 v90, |v38|, v39, v184
	v_add_f32_e32 v38, v38, v185
	v_add_f32_e32 v40, v40, v185
	v_fma_f32 v75, |v36|, v39, v184
	v_fma_f32 v83, |v37|, v39, v184
	v_add_f32_e32 v36, v36, v185
	v_add_f32_e32 v37, v37, v185
	v_fma_f32 v91, |v38|, v39, v184
	v_add_f32_e32 v38, v38, v185
	v_fma_f32 v68, |v40|, v39, v184
	v_add_f32_e32 v40, v40, v185
	v_fma_f32 v76, |v36|, v39, v184
	v_fma_f32 v84, |v37|, v39, v184
	v_add_f32_e32 v36, v36, v185
	v_fma_f32 v92, |v38|, v39, v184
	v_add_f32_e32 v37, v37, v185
	v_add_f32_e32 v38, v38, v185
	v_fma_f32 v69, |v40|, v39, v184
	v_add_f32_e32 v40, v40, v185
	v_fma_f32 v77, |v36|, v39, v184
	v_add_f32_e32 v36, v36, v185
	v_fma_f32 v85, |v37|, v39, v184
	v_fma_f32 v93, |v38|, v39, v184
	v_add_f32_e32 v37, v37, v185
	v_add_f32_e32 v38, v38, v185
	v_fma_f32 v70, |v40|, v39, v184
	v_fma_f32 v78, |v36|, v39, v184
	v_add_f32_e32 v40, v40, v185
	v_add_f32_e32 v36, v36, v185
	v_fma_f32 v86, |v37|, v39, v184
	v_fma_f32 v94, |v38|, v39, v184
	v_add_f32_e32 v37, v37, v185
	v_add_f32_e32 v38, v38, v185
	v_fma_f32 v71, |v40|, v39, v184
	v_fma_f32 v79, |v36|, v39, v184
	v_fma_f32 v87, |v37|, v39, v184
	v_fma_f32 v95, |v38|, v39, v184
